# gate and barrier spin loops poll every 64 cycles instead of every 512 (s_sleep 1)
# speedup vs baseline: 1.0027x; 1.0002x over previous
.LBB0_33:
	s_and_b32 s16, s20, 0xff
	s_mov_b64 s[14:15], -1
	s_cmp_lg_u32 s16, 0
	s_mov_b64 s[18:19], -1
	s_sleep 1
	s_cbranch_scc0 .LBB0_36
	s_and_b64 vcc, exec, s[18:19]
	s_cbranch_vccz .LBB0_32

.LBB0_71:
	s_and_b32 s14, s18, 0xff
	s_mov_b64 s[12:13], -1
	s_cmp_lg_u32 s14, 0
	s_mov_b64 s[16:17], -1
	s_sleep 1
	s_cbranch_scc0 .LBB0_74
	s_and_b64 vcc, exec, s[16:17]
	s_cbranch_vccz .LBB0_70

.LBB0_242:
	s_and_b32 s12, s16, 0xff
	s_mov_b64 s[10:11], -1
	s_cmp_lg_u32 s12, 0
	s_mov_b64 s[14:15], -1
	s_sleep 1
	s_cbranch_scc0 .LBB0_245
	s_and_b64 vcc, exec, s[14:15]
	s_cbranch_vccz .LBB0_241

.LBB0_297:
	s_and_b32 s19, s9, 0xff
	s_mov_b64 s[34:35], -1
	s_cmp_lg_u32 s19, 0
	s_mov_b64 s[38:39], -1
	s_sleep 1
	s_cbranch_scc0 .LBB0_300
	s_and_b64 vcc, exec, s[38:39]
	s_cbranch_vccz .LBB0_296

.LBB0_338:
	s_and_b32 s18, s22, 0xff
	s_mov_b64 s[16:17], -1
	s_cmp_lg_u32 s18, 0
	s_mov_b64 s[20:21], -1
	s_sleep 1
	s_cbranch_scc0 .LBB0_341
	s_and_b64 vcc, exec, s[20:21]
	s_cbranch_vccz .LBB0_337

.LBB0_372:
	s_and_b32 s23, s21, 0xff
	s_mov_b64 s[36:37], -1
	s_cmp_lg_u32 s23, 0
	s_mov_b64 s[40:41], -1
	s_sleep 1
	s_cbranch_scc0 .LBB0_375
	s_and_b64 vcc, exec, s[40:41]
	s_cbranch_vccz .LBB0_371

.LBB0_405:
	s_and_b32 s28, s34, 0xff
	s_mov_b64 s[26:27], -1
	s_cmp_lg_u32 s28, 0
	s_mov_b64 s[30:31], -1
	s_sleep 1
	s_cbranch_scc0 .LBB0_408
	s_and_b64 vcc, exec, s[30:31]
	s_cbranch_vccz .LBB0_404

.LBB0_487:
	s_and_b32 s26, s9, 0xff
	s_mov_b64 s[24:25], -1
	s_cmp_lg_u32 s26, 0
	s_mov_b64 s[28:29], -1
	s_sleep 1
	s_cbranch_scc0 .LBB0_490
	s_and_b64 vcc, exec, s[28:29]
	s_cbranch_vccz .LBB0_486

.LBB0_1060:
	s_and_b32 s14, s23, 0xff
	s_mov_b64 s[12:13], -1
	s_cmp_lg_u32 s14, 0
	s_mov_b64 s[16:17], -1
	s_sleep 1
	s_cbranch_scc0 .LBB0_1063
	s_and_b64 vcc, exec, s[16:17]
	s_cbranch_vccz .LBB0_1059
